# swiglu epilogue: wait-state nops that no longer follow a transcendental op removed (34 per tile)
# baseline (speedup 1.0000x reference)
.LBB0_402:
	s_add_u32 s20, s18, 0xfffc0080
	s_addc_u32 s21, s19, -1
	s_add_i32 s41, 0, 0x10000
	ds_read_b128 v[138:141], v218
	ds_read_b128 v[148:151], v218 offset:1024
	ds_read_b128 v[152:155], v218 offset:2048
	ds_read_b128 v[156:159], v218 offset:3072
	s_cmp_eq_u32 s40, 12
	s_cselect_b32 s23, s1, s21
	s_cselect_b32 s22, s9, s20
	s_cselect_b32 s21, s11, s39
	s_cselect_b32 s20, s33, s38
	s_add_i32 m0, s17, 0xc000
	ds_read_b128 v[160:163], v146
	ds_read_b128 v[164:167], v146 offset:1024
	ds_read_b128 v[168:171], v146 offset:2048
	ds_read_b128 v[172:175], v146 offset:3072
	ds_read_b128 v[176:179], v146 offset:4096
	ds_read_b128 v[180:183], v146 offset:5120
	ds_read_b128 v[184:187], v146 offset:6144
	ds_read_b128 v[188:191], v146 offset:7168
	global_load_lds_dwordx4 v136, s[18:19]
	s_add_i32 m0, s17, 0xe000
	s_nop 0
	global_load_lds_dwordx4 v134, s[18:19]
	s_waitcnt lgkmcnt(8)
	s_barrier
	s_waitcnt lgkmcnt(0)
	v_mfma_f32_16x16x32_bf16 v[124:127], v[138:141], v[160:163], v[124:127]
	v_mfma_f32_16x16x32_bf16 v[116:119], v[152:155], v[160:163], v[116:119]
	v_mfma_f32_16x16x32_bf16 v[108:111], v[138:141], v[168:171], v[108:111]
	v_mfma_f32_16x16x32_bf16 v[100:103], v[152:155], v[168:171], v[100:103]
	v_mfma_f32_16x16x32_bf16 v[92:95], v[138:141], v[176:179], v[92:95]
	v_mfma_f32_16x16x32_bf16 v[84:87], v[152:155], v[176:179], v[84:87]
	v_mfma_f32_16x16x32_bf16 v[76:79], v[138:141], v[184:187], v[76:79]
	v_mfma_f32_16x16x32_bf16 v[68:71], v[152:155], v[184:187], v[68:71]
	v_mfma_f32_16x16x32_bf16 v[124:127], v[148:151], v[164:167], v[124:127]
	v_mfma_f32_16x16x32_bf16 v[116:119], v[156:159], v[164:167], v[116:119]
	v_mfma_f32_16x16x32_bf16 v[108:111], v[148:151], v[172:175], v[108:111]
	v_mfma_f32_16x16x32_bf16 v[100:103], v[156:159], v[172:175], v[100:103]
	v_mfma_f32_16x16x32_bf16 v[92:95], v[148:151], v[180:183], v[92:95]
	v_mfma_f32_16x16x32_bf16 v[84:87], v[156:159], v[180:183], v[84:87]
	v_mfma_f32_16x16x32_bf16 v[76:79], v[148:151], v[188:191], v[76:79]
	v_mfma_f32_16x16x32_bf16 v[68:71], v[156:159], v[188:191], v[68:71]
	s_barrier
	s_add_i32 s44, 0, 0x14000
	s_add_i32 s41, s41, s28
	ds_read_b128 v[198:201], v219
	ds_read_b128 v[206:209], v219 offset:1024
	ds_read_b128 v[210:213], v219 offset:2048
	ds_read_b128 v[214:217], v219 offset:3072
	s_mov_b32 m0, s41
	s_nop 0
	global_load_lds_dwordx4 v192, s[20:21]
	s_add_i32 m0, s41, 0x2000
	s_nop 0
	global_load_lds_dwordx4 v128, s[20:21]
	s_barrier
	s_waitcnt lgkmcnt(0)
	v_mfma_f32_16x16x32_bf16 v[120:123], v[198:201], v[160:163], v[120:123]
	v_mfma_f32_16x16x32_bf16 v[112:115], v[210:213], v[160:163], v[112:115]
	v_mfma_f32_16x16x32_bf16 v[104:107], v[198:201], v[168:171], v[104:107]
	v_mfma_f32_16x16x32_bf16 v[96:99], v[210:213], v[168:171], v[96:99]
	v_mfma_f32_16x16x32_bf16 v[88:91], v[198:201], v[176:179], v[88:91]
	v_mfma_f32_16x16x32_bf16 v[80:83], v[210:213], v[176:179], v[80:83]
	v_mfma_f32_16x16x32_bf16 v[72:75], v[198:201], v[184:187], v[72:75]
	v_mfma_f32_16x16x32_bf16 v[64:67], v[210:213], v[184:187], v[64:67]
	v_mfma_f32_16x16x32_bf16 v[120:123], v[206:209], v[164:167], v[120:123]
	v_mfma_f32_16x16x32_bf16 v[112:115], v[214:217], v[164:167], v[112:115]
	v_mfma_f32_16x16x32_bf16 v[104:107], v[206:209], v[172:175], v[104:107]
	v_mfma_f32_16x16x32_bf16 v[96:99], v[214:217], v[172:175], v[96:99]
	v_mfma_f32_16x16x32_bf16 v[88:91], v[206:209], v[180:183], v[88:91]
	v_mfma_f32_16x16x32_bf16 v[80:83], v[214:217], v[180:183], v[80:83]
	v_mfma_f32_16x16x32_bf16 v[72:75], v[206:209], v[188:191], v[72:75]
	v_mfma_f32_16x16x32_bf16 v[64:67], v[214:217], v[188:191], v[64:67]
	s_mov_b32 m0, s17
	s_add_u32 vcc_lo, s22, 0x80
	s_addc_u32 vcc_hi, s23, 0
	s_barrier
	ds_read_b128 v[160:163], v146 offset:16384
	ds_read_b128 v[164:167], v146 offset:17408
	ds_read_b128 v[168:171], v146 offset:18432
	ds_read_b128 v[172:175], v146 offset:19456
	ds_read_b128 v[176:179], v146 offset:20480
	ds_read_b128 v[180:183], v146 offset:21504
	ds_read_b128 v[184:187], v146 offset:22528
	ds_read_b128 v[188:191], v146 offset:23552
	global_load_lds_dwordx4 v132, s[22:23]
	s_mov_b32 m0, s29
	s_nop 0
	global_load_lds_dwordx4 v130, s[22:23]
	s_barrier
	s_waitcnt lgkmcnt(0)
	v_mfma_f32_16x16x32_bf16 v[60:63], v[138:141], v[160:163], v[60:63]
	v_mfma_f32_16x16x32_bf16 v[52:55], v[152:155], v[160:163], v[52:55]
	v_mfma_f32_16x16x32_bf16 v[44:47], v[138:141], v[168:171], v[44:47]
	v_mfma_f32_16x16x32_bf16 v[36:39], v[152:155], v[168:171], v[36:39]
	v_mfma_f32_16x16x32_bf16 v[28:31], v[138:141], v[176:179], v[28:31]
	v_mfma_f32_16x16x32_bf16 v[20:23], v[152:155], v[176:179], v[20:23]
	v_mfma_f32_16x16x32_bf16 v[12:15], v[138:141], v[184:187], v[12:15]
	v_mfma_f32_16x16x32_bf16 v[4:7], v[152:155], v[184:187], v[4:7]
	v_mfma_f32_16x16x32_bf16 v[60:63], v[148:151], v[164:167], v[60:63]
	v_mfma_f32_16x16x32_bf16 v[52:55], v[156:159], v[164:167], v[52:55]
	v_mfma_f32_16x16x32_bf16 v[44:47], v[148:151], v[172:175], v[44:47]
	v_mfma_f32_16x16x32_bf16 v[36:39], v[156:159], v[172:175], v[36:39]
	v_mfma_f32_16x16x32_bf16 v[28:31], v[148:151], v[180:183], v[28:31]
	v_mfma_f32_16x16x32_bf16 v[20:23], v[156:159], v[180:183], v[20:23]
	v_mfma_f32_16x16x32_bf16 v[12:15], v[148:151], v[188:191], v[12:15]
	v_mfma_f32_16x16x32_bf16 v[4:7], v[156:159], v[188:191], v[4:7]
	s_barrier
	s_add_u32 s42, s20, 0x40000
	s_addc_u32 s43, s21, 0
	s_add_i32 s41, s44, s28
	s_mov_b32 m0, s41
	s_nop 0
	global_load_lds_dwordx4 v192, s[42:43]
	s_add_i32 m0, s41, 0x2000
	s_nop 0
	global_load_lds_dwordx4 v128, s[42:43]
	s_waitcnt vmcnt(6)
	s_barrier
	v_mfma_f32_16x16x32_bf16 v[56:59], v[198:201], v[160:163], v[56:59]
	v_mfma_f32_16x16x32_bf16 v[48:51], v[210:213], v[160:163], v[48:51]
	v_mfma_f32_16x16x32_bf16 v[40:43], v[198:201], v[168:171], v[40:43]
	v_mfma_f32_16x16x32_bf16 v[32:35], v[210:213], v[168:171], v[32:35]
	v_mfma_f32_16x16x32_bf16 v[24:27], v[198:201], v[176:179], v[24:27]
	v_mfma_f32_16x16x32_bf16 v[16:19], v[210:213], v[176:179], v[16:19]
	v_mfma_f32_16x16x32_bf16 v[8:11], v[198:201], v[184:187], v[8:11]
	v_mfma_f32_16x16x32_bf16 v[0:3], v[210:213], v[184:187], v[0:3]
	v_mfma_f32_16x16x32_bf16 v[56:59], v[206:209], v[164:167], v[56:59]
	v_mfma_f32_16x16x32_bf16 v[48:51], v[214:217], v[164:167], v[48:51]
	v_mfma_f32_16x16x32_bf16 v[40:43], v[206:209], v[172:175], v[40:43]
	v_mfma_f32_16x16x32_bf16 v[32:35], v[214:217], v[172:175], v[32:35]
	v_mfma_f32_16x16x32_bf16 v[24:27], v[206:209], v[180:183], v[24:27]
	v_mfma_f32_16x16x32_bf16 v[16:19], v[214:217], v[180:183], v[16:19]
	v_mfma_f32_16x16x32_bf16 v[8:11], v[206:209], v[188:191], v[8:11]
	v_mfma_f32_16x16x32_bf16 v[0:3], v[214:217], v[188:191], v[0:3]
	s_add_i32 s41, 0, 0x18000
	s_barrier
	ds_read_b128 v[138:141], v220
	ds_read_b128 v[148:151], v220 offset:1024
	ds_read_b128 v[152:155], v220 offset:2048
	ds_read_b128 v[156:159], v220 offset:3072
	s_add_u32 s22, s22, 0x40000
	s_addc_u32 s23, s23, 0
	s_mov_b32 m0, s30
	ds_read_b128 v[160:163], v146 offset:32768
	ds_read_b128 v[164:167], v146 offset:33792
	ds_read_b128 v[168:171], v146 offset:34816
	ds_read_b128 v[172:175], v146 offset:35840
	ds_read_b128 v[176:179], v146 offset:36864
	ds_read_b128 v[180:183], v146 offset:37888
	ds_read_b128 v[184:187], v146 offset:38912
	ds_read_b128 v[188:191], v146 offset:39936
	global_load_lds_dwordx4 v132, s[22:23]
	s_mov_b32 m0, s31
	s_nop 0
	global_load_lds_dwordx4 v130, s[22:23]
	s_waitcnt lgkmcnt(8)
	s_barrier
	s_waitcnt lgkmcnt(0)
	v_mfma_f32_16x16x32_bf16 v[124:127], v[138:141], v[160:163], v[124:127]
	v_mfma_f32_16x16x32_bf16 v[116:119], v[152:155], v[160:163], v[116:119]
	v_mfma_f32_16x16x32_bf16 v[108:111], v[138:141], v[168:171], v[108:111]
	v_mfma_f32_16x16x32_bf16 v[100:103], v[152:155], v[168:171], v[100:103]
	v_mfma_f32_16x16x32_bf16 v[92:95], v[138:141], v[176:179], v[92:95]
	v_mfma_f32_16x16x32_bf16 v[84:87], v[152:155], v[176:179], v[84:87]
	v_mfma_f32_16x16x32_bf16 v[76:79], v[138:141], v[184:187], v[76:79]
	v_mfma_f32_16x16x32_bf16 v[68:71], v[152:155], v[184:187], v[68:71]
	v_mfma_f32_16x16x32_bf16 v[124:127], v[148:151], v[164:167], v[124:127]
	v_mfma_f32_16x16x32_bf16 v[116:119], v[156:159], v[164:167], v[116:119]
	v_mfma_f32_16x16x32_bf16 v[108:111], v[148:151], v[172:175], v[108:111]
	v_mfma_f32_16x16x32_bf16 v[100:103], v[156:159], v[172:175], v[100:103]
	v_mfma_f32_16x16x32_bf16 v[92:95], v[148:151], v[180:183], v[92:95]
	v_mfma_f32_16x16x32_bf16 v[84:87], v[156:159], v[180:183], v[84:87]
	v_mfma_f32_16x16x32_bf16 v[76:79], v[148:151], v[188:191], v[76:79]
	v_mfma_f32_16x16x32_bf16 v[68:71], v[156:159], v[188:191], v[68:71]
	s_barrier
	s_add_i32 s22, 0, 0x1c000
	s_add_i32 s23, s41, s28
	s_add_u32 s100, s20, 0x80
	s_addc_u32 s101, s21, 0
	s_mov_b32 m0, s23
	ds_read_b128 v[198:201], v221
	ds_read_b128 v[206:209], v221 offset:1024
	ds_read_b128 v[210:213], v221 offset:2048
	ds_read_b128 v[214:217], v221 offset:3072
	global_load_lds_dwordx4 v192, s[100:101]
	s_add_i32 m0, s23, 0x2000
	s_nop 0
	global_load_lds_dwordx4 v128, s[100:101]
	s_barrier
	s_waitcnt lgkmcnt(0)
	v_mfma_f32_16x16x32_bf16 v[120:123], v[198:201], v[160:163], v[120:123]
	v_mfma_f32_16x16x32_bf16 v[112:115], v[210:213], v[160:163], v[112:115]
	v_mfma_f32_16x16x32_bf16 v[104:107], v[198:201], v[168:171], v[104:107]
	v_mfma_f32_16x16x32_bf16 v[96:99], v[210:213], v[168:171], v[96:99]
	v_mfma_f32_16x16x32_bf16 v[88:91], v[198:201], v[176:179], v[88:91]
	v_mfma_f32_16x16x32_bf16 v[80:83], v[210:213], v[176:179], v[80:83]
	v_mfma_f32_16x16x32_bf16 v[72:75], v[198:201], v[184:187], v[72:75]
	v_mfma_f32_16x16x32_bf16 v[64:67], v[210:213], v[184:187], v[64:67]
	v_mfma_f32_16x16x32_bf16 v[120:123], v[206:209], v[164:167], v[120:123]
	v_mfma_f32_16x16x32_bf16 v[112:115], v[214:217], v[164:167], v[112:115]
	v_mfma_f32_16x16x32_bf16 v[104:107], v[206:209], v[172:175], v[104:107]
	v_mfma_f32_16x16x32_bf16 v[96:99], v[214:217], v[172:175], v[96:99]
	v_mfma_f32_16x16x32_bf16 v[88:91], v[206:209], v[180:183], v[88:91]
	v_mfma_f32_16x16x32_bf16 v[80:83], v[214:217], v[180:183], v[80:83]
	v_mfma_f32_16x16x32_bf16 v[72:75], v[206:209], v[188:191], v[72:75]
	v_mfma_f32_16x16x32_bf16 v[64:67], v[214:217], v[188:191], v[64:67]
	s_mov_b32 m0, s34
	s_barrier
	ds_read_b128 v[160:163], v146 offset:49152
	ds_read_b128 v[164:167], v146 offset:50176
	ds_read_b128 v[168:171], v146 offset:51200
	ds_read_b128 v[172:175], v146 offset:52224
	ds_read_b128 v[176:179], v146 offset:53248
	ds_read_b128 v[180:183], v146 offset:54272
	ds_read_b128 v[184:187], v146 offset:55296
	ds_read_b128 v[188:191], v146 offset:56320
	global_load_lds_dwordx4 v132, vcc
	s_mov_b32 m0, s35
	s_nop 0
	global_load_lds_dwordx4 v130, vcc
	s_barrier
	s_waitcnt lgkmcnt(0)
	v_mfma_f32_16x16x32_bf16 v[60:63], v[138:141], v[160:163], v[60:63]
	v_mfma_f32_16x16x32_bf16 v[52:55], v[152:155], v[160:163], v[52:55]
	v_mfma_f32_16x16x32_bf16 v[44:47], v[138:141], v[168:171], v[44:47]
	v_mfma_f32_16x16x32_bf16 v[36:39], v[152:155], v[168:171], v[36:39]
	v_mfma_f32_16x16x32_bf16 v[28:31], v[138:141], v[176:179], v[28:31]
	v_mfma_f32_16x16x32_bf16 v[20:23], v[152:155], v[176:179], v[20:23]
	v_mfma_f32_16x16x32_bf16 v[12:15], v[138:141], v[184:187], v[12:15]
	v_mfma_f32_16x16x32_bf16 v[4:7], v[152:155], v[184:187], v[4:7]
	v_mfma_f32_16x16x32_bf16 v[60:63], v[148:151], v[164:167], v[60:63]
	v_mfma_f32_16x16x32_bf16 v[52:55], v[156:159], v[164:167], v[52:55]
	v_mfma_f32_16x16x32_bf16 v[44:47], v[148:151], v[172:175], v[44:47]
	v_mfma_f32_16x16x32_bf16 v[36:39], v[156:159], v[172:175], v[36:39]
	v_mfma_f32_16x16x32_bf16 v[28:31], v[148:151], v[180:183], v[28:31]
	v_mfma_f32_16x16x32_bf16 v[20:23], v[156:159], v[180:183], v[20:23]
	v_mfma_f32_16x16x32_bf16 v[12:15], v[148:151], v[188:191], v[12:15]
	v_mfma_f32_16x16x32_bf16 v[4:7], v[156:159], v[188:191], v[4:7]
	s_barrier
	s_add_u32 s20, s20, 0x40080
	s_addc_u32 s21, s21, 0
	s_add_i32 s22, s22, s28
	s_mov_b32 m0, s22
	s_nop 0
	global_load_lds_dwordx4 v192, s[20:21]
	s_add_i32 m0, s22, 0x2000
	s_nop 0
	global_load_lds_dwordx4 v128, s[20:21]
	s_waitcnt vmcnt(6)
	s_barrier
	v_mfma_f32_16x16x32_bf16 v[56:59], v[198:201], v[160:163], v[56:59]
	v_mfma_f32_16x16x32_bf16 v[48:51], v[210:213], v[160:163], v[48:51]
	v_mfma_f32_16x16x32_bf16 v[40:43], v[198:201], v[168:171], v[40:43]
	v_mfma_f32_16x16x32_bf16 v[32:35], v[210:213], v[168:171], v[32:35]
	v_mfma_f32_16x16x32_bf16 v[24:27], v[198:201], v[176:179], v[24:27]
	v_mfma_f32_16x16x32_bf16 v[16:19], v[210:213], v[176:179], v[16:19]
	v_mfma_f32_16x16x32_bf16 v[8:11], v[198:201], v[184:187], v[8:11]
	v_mfma_f32_16x16x32_bf16 v[0:3], v[210:213], v[184:187], v[0:3]
	v_mfma_f32_16x16x32_bf16 v[56:59], v[206:209], v[164:167], v[56:59]
	v_mfma_f32_16x16x32_bf16 v[48:51], v[214:217], v[164:167], v[48:51]
	v_mfma_f32_16x16x32_bf16 v[40:43], v[206:209], v[172:175], v[40:43]
	v_mfma_f32_16x16x32_bf16 v[32:35], v[214:217], v[172:175], v[32:35]
	v_mfma_f32_16x16x32_bf16 v[24:27], v[206:209], v[180:183], v[24:27]
	v_mfma_f32_16x16x32_bf16 v[16:19], v[214:217], v[180:183], v[16:19]
	v_mfma_f32_16x16x32_bf16 v[8:11], v[206:209], v[188:191], v[8:11]
	v_mfma_f32_16x16x32_bf16 v[0:3], v[214:217], v[188:191], v[0:3]
	s_add_i32 s40, s40, 2
	s_add_u32 s38, s38, 0x100
	s_addc_u32 s39, s39, 0
	s_add_u32 s18, s18, 0x100
	s_addc_u32 s19, s19, 0
	s_cmp_gt_u32 s40, 13
	s_barrier
	s_cbranch_scc0 .LBB0_402
	v_mov_b32_e32 v139, v252
	s_lshl_b32 s9, s16, 8
	v_readfirstlane_b32 s1, v139
	s_ashr_i32 s11, s1, 2
	s_andn2_b32 s11, s11, 63
	s_lshr_b32 s1, s1, 1
	s_add_i32 s11, s11, s9
	s_lshl_b32 s0, s0, 7
	s_and_b32 s1, s1, 0x60
	v_and_or_b32 v138, v139, 15, s11
	s_or_b32 s0, s1, s0
	v_lshrrev_b32_e32 v139, 1, v139
	v_and_or_b32 v142, v139, 24, s0
	v_ashrrev_i32_e32 v139, 31, v138
	v_lshl_add_u64 v[140:141], v[138:139], 2, s[6:7]
	v_pk_mul_f32 v[120:121], v[124:125], v[120:121]
	v_pk_mul_f32 v[122:123], v[126:127], v[122:123]
	v_pk_mul_f32 v[112:113], v[116:117], v[112:113]
	v_pk_mul_f32 v[114:115], v[118:119], v[114:115]
	v_ashrrev_i32_e32 v143, 31, v142
	s_movk_i32 s9, 0x1600
	v_pk_mul_f32 v[104:105], v[108:109], v[104:105]
	v_pk_mul_f32 v[106:107], v[110:111], v[106:107]
	v_pk_mul_f32 v[96:97], v[100:101], v[96:97]
	v_or_b32_e32 v150, 16, v138
	v_pk_mul_f32 v[98:99], v[102:103], v[98:99]
	v_pk_mul_f32 v[88:89], v[92:93], v[88:89]
	v_pk_mul_f32 v[90:91], v[94:95], v[90:91]
	v_pk_mul_f32 v[80:81], v[84:85], v[80:81]
	v_or_b32_e32 v148, 32, v138
	v_pk_mul_f32 v[82:83], v[86:87], v[82:83]
	v_pk_mul_f32 v[72:73], v[76:77], v[72:73]
	v_pk_mul_f32 v[74:75], v[78:79], v[74:75]
	v_pk_mul_f32 v[64:65], v[68:69], v[64:65]
	v_or_b32_e32 v139, 48, v138
	v_pk_mul_f32 v[66:67], v[70:71], v[66:67]
	v_pk_mul_f32 v[56:57], v[60:61], v[56:57]
	v_pk_mul_f32 v[58:59], v[62:63], v[58:59]
	v_pk_mul_f32 v[48:49], v[52:53], v[48:49]
	v_pk_mul_f32 v[50:51], v[54:55], v[50:51]
	v_pk_mul_f32 v[40:41], v[44:45], v[40:41]
	v_pk_mul_f32 v[42:43], v[46:47], v[42:43]
	v_pk_mul_f32 v[32:33], v[36:37], v[32:33]
	v_pk_mul_f32 v[34:35], v[38:39], v[34:35]
	v_pk_mul_f32 v[24:25], v[28:29], v[24:25]
	v_pk_mul_f32 v[26:27], v[30:31], v[26:27]
	v_pk_mul_f32 v[16:17], v[20:21], v[16:17]
	v_pk_mul_f32 v[18:19], v[22:23], v[18:19]
	v_pk_mul_f32 v[8:9], v[12:13], v[8:9]
	v_pk_mul_f32 v[10:11], v[14:15], v[10:11]
	v_pk_mul_f32 v[0:1], v[4:5], v[0:1]
	v_pk_mul_f32 v[2:3], v[6:7], v[2:3]
	s_mov_b32 s16, s8
	s_mov_b64 s[18:19], s[14:15]
	s_mov_b64 s[20:21], s[12:13]
	v_fmamk_f32 v239, v231, 0x3a800000, v194
	s_nop 0
	v_rsq_f32_e32 v144, v239
	s_nop 0
	v_mul_f32_e32 v152, 0xbfb8aa3b, v144
	v_pk_mul_f32 v[156:157], v[124:125], v[152:153] op_sel_hi:[1,0]
	v_pk_mul_f32 v[154:155], v[126:127], v[152:153] op_sel_hi:[1,0]
	v_exp_f32_e32 v153, v156
	s_nop 0
	v_fma_f32 v153, v153, v239, v239
	v_rcp_f32_e32 v156, v153
	v_exp_f32_e32 v153, v157
	s_nop 0
	v_fma_f32 v153, v153, v239, v239
	v_rcp_f32_e32 v157, v153
	v_exp_f32_e32 v153, v154
	s_nop 0
	v_fma_f32 v153, v153, v239, v239
	v_rcp_f32_e32 v154, v153
	v_exp_f32_e32 v153, v155
	v_pk_mul_f32 v[120:121], v[120:121], v[156:157]
	v_fma_f32 v153, v153, v239, v239
	v_rcp_f32_e32 v155, v153
	v_cvt_pk_bf16_f32 v120, v120, v121
	v_readlane_b32 s0, v254, 29
	s_nop 0
	v_pk_mul_f32 v[122:123], v[122:123], v[154:155]
	v_readlane_b32 s1, v254, 30
	v_cvt_pk_bf16_f32 v121, v122, v123
	v_pk_mul_f32 v[124:125], v[116:117], v[152:153] op_sel_hi:[1,0]
	v_pk_mul_f32 v[122:123], v[118:119], v[152:153] op_sel_hi:[1,0]
	v_exp_f32_e32 v124, v124
	v_exp_f32_e32 v125, v125
	v_exp_f32_e32 v122, v122
	v_exp_f32_e32 v123, v123
	v_fma_f32 v124, v124, v239, v239
	v_fma_f32 v125, v125, v239, v239
	v_rcp_f32_e32 v124, v124
	v_rcp_f32_e32 v125, v125
	v_fma_f32 v122, v122, v239, v239
	v_fma_f32 v123, v123, v239, v239
	v_rcp_f32_e32 v122, v122
	v_rcp_f32_e32 v123, v123
	s_nop 0
	v_pk_mul_f32 v[112:113], v[112:113], v[124:125]
	v_pk_mul_f32 v[114:115], v[114:115], v[122:123]
	v_cvt_pk_bf16_f32 v122, v112, v113
	v_cvt_pk_bf16_f32 v123, v114, v115
	v_mul_u32_u24_e32 v116, 0x1600, v138
	v_lshlrev_b32_e32 v114, 1, v142
	v_add_u32_e32 v116, v116, v114
	global_store_dwordx4 v116, v[120:123], s[0:1]
	v_fmamk_f32 v239, v232, 0x3a800000, v194
	v_rsq_f32_e32 v116, v239
	s_nop 0
	v_mul_f32_e32 v118, 0xbfb8aa3b, v116
	v_pk_mul_f32 v[120:121], v[108:109], v[118:119] op_sel_hi:[1,0]
	v_pk_mul_f32 v[122:123], v[110:111], v[118:119] op_sel_hi:[1,0]
	v_exp_f32_e32 v117, v120
	s_nop 0
	v_fma_f32 v117, v117, v239, v239
	v_rcp_f32_e32 v120, v117
	v_exp_f32_e32 v117, v121
	s_nop 0
	v_fma_f32 v117, v117, v239, v239
	v_rcp_f32_e32 v121, v117
	v_exp_f32_e32 v117, v122
	s_nop 0
	v_fma_f32 v117, v117, v239, v239
	v_rcp_f32_e32 v122, v117
	v_exp_f32_e32 v117, v123
	s_nop 0
	v_fma_f32 v117, v117, v239, v239
	v_rcp_f32_e32 v123, v117
	s_nop 0
	v_pk_mul_f32 v[104:105], v[104:105], v[120:121]
	v_pk_mul_f32 v[106:107], v[106:107], v[122:123]
	v_cvt_pk_bf16_f32 v104, v104, v105
	v_cvt_pk_bf16_f32 v105, v106, v107
	v_pk_mul_f32 v[108:109], v[100:101], v[118:119] op_sel_hi:[1,0]
	v_pk_mul_f32 v[106:107], v[102:103], v[118:119] op_sel_hi:[1,0]
	v_exp_f32_e32 v108, v108
	v_exp_f32_e32 v109, v109
	v_exp_f32_e32 v106, v106
	v_exp_f32_e32 v107, v107
	v_fma_f32 v108, v108, v239, v239
	v_fma_f32 v109, v109, v239, v239
	v_rcp_f32_e32 v108, v108
	v_rcp_f32_e32 v109, v109
	v_fma_f32 v106, v106, v239, v239
	v_fma_f32 v107, v107, v239, v239
	v_rcp_f32_e32 v106, v106
	v_rcp_f32_e32 v107, v107
	s_nop 0
	v_pk_mul_f32 v[96:97], v[96:97], v[108:109]
	v_pk_mul_f32 v[98:99], v[98:99], v[106:107]
	v_cvt_pk_bf16_f32 v106, v96, v97
	v_mul_u32_u24_e32 v96, 0x1600, v150
	v_cvt_pk_bf16_f32 v107, v98, v99
	v_add_u32_e32 v96, v96, v114
	global_store_dwordx4 v96, v[104:107], s[0:1]
	v_fmamk_f32 v239, v233, 0x3a800000, v194
	v_rsq_f32_e32 v96, v239
	s_nop 0
	v_mov_b32_e32 v97, v96
	v_mul_f32_e32 v96, 0xbfb8aa3b, v97
	v_pk_mul_f32 v[102:103], v[92:93], v[96:97] op_sel_hi:[1,0]
	v_pk_mul_f32 v[100:101], v[94:95], v[96:97] op_sel_hi:[1,0]
	v_exp_f32_e32 v97, v102
	s_nop 0
	v_fma_f32 v97, v97, v239, v239
	v_rcp_f32_e32 v102, v97
	v_exp_f32_e32 v97, v103
	s_nop 0
	v_fma_f32 v97, v97, v239, v239
	v_rcp_f32_e32 v103, v97
	v_exp_f32_e32 v97, v100
	s_nop 0
	v_fma_f32 v97, v97, v239, v239
	v_rcp_f32_e32 v100, v97
	v_exp_f32_e32 v97, v101
	v_pk_mul_f32 v[88:89], v[88:89], v[102:103]
	v_fma_f32 v97, v97, v239, v239
	v_rcp_f32_e32 v101, v97
	v_cvt_pk_bf16_f32 v88, v88, v89
	v_pk_mul_f32 v[90:91], v[90:91], v[100:101]
	v_cvt_pk_bf16_f32 v89, v90, v91
	v_pk_mul_f32 v[92:93], v[84:85], v[96:97] op_sel_hi:[1,0]
	v_pk_mul_f32 v[90:91], v[86:87], v[96:97] op_sel_hi:[1,0]
	v_exp_f32_e32 v92, v92
	v_exp_f32_e32 v93, v93
	v_exp_f32_e32 v90, v90
	v_exp_f32_e32 v91, v91
	v_fma_f32 v92, v92, v239, v239
	v_fma_f32 v93, v93, v239, v239
	v_rcp_f32_e32 v92, v92
	v_rcp_f32_e32 v93, v93
	v_fma_f32 v90, v90, v239, v239
	v_fma_f32 v91, v91, v239, v239
	v_rcp_f32_e32 v90, v90
	v_rcp_f32_e32 v91, v91
	s_nop 0
	v_pk_mul_f32 v[80:81], v[80:81], v[92:93]
	v_pk_mul_f32 v[82:83], v[82:83], v[90:91]
	v_cvt_pk_bf16_f32 v90, v80, v81
	v_mul_u32_u24_e32 v80, 0x1600, v148
	v_cvt_pk_bf16_f32 v91, v82, v83
	v_add_u32_e32 v80, v80, v114
	global_store_dwordx4 v80, v[88:91], s[0:1]
	v_fmamk_f32 v239, v234, 0x3a800000, v194
	v_rsq_f32_e32 v80, v239
	s_nop 0
	v_mov_b32_e32 v81, v80
	v_mul_f32_e32 v80, 0xbfb8aa3b, v81
	v_pk_mul_f32 v[86:87], v[76:77], v[80:81] op_sel_hi:[1,0]
	v_pk_mul_f32 v[84:85], v[78:79], v[80:81] op_sel_hi:[1,0]
	v_exp_f32_e32 v81, v86
	s_nop 0
	v_fma_f32 v81, v81, v239, v239
	v_rcp_f32_e32 v86, v81
	v_exp_f32_e32 v81, v87
	s_nop 0
	v_fma_f32 v81, v81, v239, v239
	v_rcp_f32_e32 v87, v81
	v_exp_f32_e32 v81, v84
	s_nop 0
	v_fma_f32 v81, v81, v239, v239
	v_rcp_f32_e32 v84, v81
	v_exp_f32_e32 v81, v85
	v_pk_mul_f32 v[72:73], v[72:73], v[86:87]
	v_fma_f32 v81, v81, v239, v239
	v_rcp_f32_e32 v85, v81
	v_cvt_pk_bf16_f32 v72, v72, v73
	v_pk_mul_f32 v[74:75], v[74:75], v[84:85]
	v_cvt_pk_bf16_f32 v73, v74, v75
	v_pk_mul_f32 v[76:77], v[68:69], v[80:81] op_sel_hi:[1,0]
	v_pk_mul_f32 v[74:75], v[70:71], v[80:81] op_sel_hi:[1,0]
	v_exp_f32_e32 v76, v76
	v_exp_f32_e32 v77, v77
	v_exp_f32_e32 v74, v74
	v_exp_f32_e32 v75, v75
	v_fma_f32 v76, v76, v239, v239
	v_fma_f32 v77, v77, v239, v239
	v_rcp_f32_e32 v76, v76
	v_rcp_f32_e32 v77, v77
	v_fma_f32 v74, v74, v239, v239
	v_fma_f32 v75, v75, v239, v239
	v_rcp_f32_e32 v74, v74
	v_rcp_f32_e32 v75, v75
	s_nop 0
	v_pk_mul_f32 v[64:65], v[64:65], v[76:77]
	v_add_u32_e32 v69, 0x90, v138
	v_pk_mul_f32 v[66:67], v[66:67], v[74:75]
	v_cvt_pk_bf16_f32 v74, v64, v65
	v_mul_u32_u24_e32 v64, 0x1600, v139
	v_cvt_pk_bf16_f32 v75, v66, v67
	v_add_u32_e32 v64, v64, v114
	global_store_dwordx4 v64, v[72:75], s[0:1]
	v_add_u32_e32 v67, 0x80, v138
	v_add_u32_e32 v66, 0xa0, v138
	v_add_u32_e32 v64, 0xb0, v138
	v_fmamk_f32 v239, v235, 0x3a800000, v194
	v_rsq_f32_e32 v68, v239
	s_nop 0
	v_mov_b32_e32 v70, v68
	v_mul_f32_e32 v68, 0xbfb8aa3b, v70
	v_pk_mul_f32 v[74:75], v[60:61], v[68:69] op_sel_hi:[1,0]
	v_pk_mul_f32 v[72:73], v[62:63], v[68:69] op_sel_hi:[1,0]
	v_exp_f32_e32 v74, v74
	v_exp_f32_e32 v75, v75
	v_exp_f32_e32 v72, v72
	v_exp_f32_e32 v73, v73
	v_fma_f32 v74, v74, v239, v239
	v_fma_f32 v75, v75, v239, v239
	v_rcp_f32_e32 v74, v74
	v_rcp_f32_e32 v75, v75
	v_fma_f32 v72, v72, v239, v239
	v_fma_f32 v73, v73, v239, v239
	v_rcp_f32_e32 v72, v72
	v_rcp_f32_e32 v73, v73
	s_nop 0
	s_nop 0
	v_pk_mul_f32 v[56:57], v[56:57], v[74:75]
	v_pk_mul_f32 v[58:59], v[58:59], v[72:73]
	v_cvt_pk_bf16_f32 v56, v56, v57
	v_cvt_pk_bf16_f32 v57, v58, v59
	v_pk_mul_f32 v[60:61], v[52:53], v[68:69] op_sel_hi:[1,0]
	v_pk_mul_f32 v[58:59], v[54:55], v[68:69] op_sel_hi:[1,0]
	v_exp_f32_e32 v60, v60
	v_exp_f32_e32 v61, v61
	v_exp_f32_e32 v58, v58
	v_exp_f32_e32 v59, v59
	v_fma_f32 v60, v60, v239, v239
	v_fma_f32 v61, v61, v239, v239
	v_rcp_f32_e32 v60, v60
	v_rcp_f32_e32 v61, v61
	v_fma_f32 v58, v58, v239, v239
	v_fma_f32 v59, v59, v239, v239
	v_rcp_f32_e32 v58, v58
	v_rcp_f32_e32 v59, v59
	s_nop 0
	v_pk_mul_f32 v[48:49], v[48:49], v[60:61]
	v_pk_mul_f32 v[50:51], v[50:51], v[58:59]
	v_cvt_pk_bf16_f32 v58, v48, v49
	v_mul_u32_u24_e32 v48, 0x1600, v67
	v_cvt_pk_bf16_f32 v59, v50, v51
	v_add_u32_e32 v48, v48, v114
	global_store_dwordx4 v48, v[56:59], s[0:1]
	v_fmamk_f32 v239, v236, 0x3a800000, v194
	v_rsq_f32_e32 v48, v239
	s_nop 0
	v_mov_b32_e32 v49, v48
	v_mul_f32_e32 v48, 0xbfb8aa3b, v49
	v_pk_mul_f32 v[54:55], v[44:45], v[48:49] op_sel_hi:[1,0]
	v_pk_mul_f32 v[52:53], v[46:47], v[48:49] op_sel_hi:[1,0]
	v_exp_f32_e32 v49, v54
	s_nop 0
	v_fma_f32 v49, v49, v239, v239
	v_rcp_f32_e32 v54, v49
	v_exp_f32_e32 v49, v55
	s_nop 0
	v_fma_f32 v49, v49, v239, v239
	v_rcp_f32_e32 v55, v49
	v_exp_f32_e32 v49, v52
	s_nop 0
	v_fma_f32 v49, v49, v239, v239
	v_rcp_f32_e32 v52, v49
	v_exp_f32_e32 v49, v53
	v_pk_mul_f32 v[40:41], v[40:41], v[54:55]
	v_fma_f32 v49, v49, v239, v239
	v_rcp_f32_e32 v53, v49
	v_cvt_pk_bf16_f32 v40, v40, v41
	v_pk_mul_f32 v[42:43], v[42:43], v[52:53]
	v_cvt_pk_bf16_f32 v41, v42, v43
	v_pk_mul_f32 v[44:45], v[36:37], v[48:49] op_sel_hi:[1,0]
	v_pk_mul_f32 v[42:43], v[38:39], v[48:49] op_sel_hi:[1,0]
	v_exp_f32_e32 v44, v44
	v_exp_f32_e32 v45, v45
	v_exp_f32_e32 v42, v42
	v_exp_f32_e32 v43, v43
	v_fma_f32 v44, v44, v239, v239
	v_fma_f32 v45, v45, v239, v239
	v_rcp_f32_e32 v44, v44
	v_rcp_f32_e32 v45, v45
	v_fma_f32 v42, v42, v239, v239
	v_fma_f32 v43, v43, v239, v239
	v_rcp_f32_e32 v42, v42
	v_rcp_f32_e32 v43, v43
	s_nop 0
	v_pk_mul_f32 v[32:33], v[32:33], v[44:45]
	v_pk_mul_f32 v[34:35], v[34:35], v[42:43]
	v_cvt_pk_bf16_f32 v42, v32, v33
	v_mul_u32_u24_e32 v32, 0x1600, v69
	v_cvt_pk_bf16_f32 v43, v34, v35
	v_add_u32_e32 v32, v32, v114
	global_store_dwordx4 v32, v[40:43], s[0:1]
	v_fmamk_f32 v239, v237, 0x3a800000, v194
	v_rsq_f32_e32 v32, v239
	s_nop 0
	v_mov_b32_e32 v33, v32
	v_mul_f32_e32 v32, 0xbfb8aa3b, v33
	v_pk_mul_f32 v[38:39], v[28:29], v[32:33] op_sel_hi:[1,0]
	v_pk_mul_f32 v[36:37], v[30:31], v[32:33] op_sel_hi:[1,0]
	v_exp_f32_e32 v33, v38
	s_nop 0
	v_fma_f32 v33, v33, v239, v239
	v_rcp_f32_e32 v38, v33
	v_exp_f32_e32 v33, v39
	s_nop 0
	v_fma_f32 v33, v33, v239, v239
	v_rcp_f32_e32 v39, v33
	v_exp_f32_e32 v33, v36
	s_nop 0
	v_fma_f32 v33, v33, v239, v239
	v_rcp_f32_e32 v36, v33
	v_exp_f32_e32 v33, v37
	v_pk_mul_f32 v[24:25], v[24:25], v[38:39]
	v_fma_f32 v33, v33, v239, v239
	v_rcp_f32_e32 v37, v33
	v_cvt_pk_bf16_f32 v24, v24, v25
	v_pk_mul_f32 v[26:27], v[26:27], v[36:37]
	v_cvt_pk_bf16_f32 v25, v26, v27
	v_pk_mul_f32 v[28:29], v[20:21], v[32:33] op_sel_hi:[1,0]
	v_pk_mul_f32 v[26:27], v[22:23], v[32:33] op_sel_hi:[1,0]
	v_exp_f32_e32 v28, v28
	v_exp_f32_e32 v29, v29
	v_exp_f32_e32 v26, v26
	v_exp_f32_e32 v27, v27
	v_fma_f32 v28, v28, v239, v239
	v_fma_f32 v29, v29, v239, v239
	v_rcp_f32_e32 v28, v28
	v_rcp_f32_e32 v29, v29
	v_fma_f32 v26, v26, v239, v239
	v_fma_f32 v27, v27, v239, v239
	v_rcp_f32_e32 v26, v26
	v_rcp_f32_e32 v27, v27
	s_nop 0
	v_pk_mul_f32 v[16:17], v[16:17], v[28:29]
	v_pk_mul_f32 v[18:19], v[18:19], v[26:27]
	v_cvt_pk_bf16_f32 v26, v16, v17
	v_mul_u32_u24_e32 v16, 0x1600, v66
	v_cvt_pk_bf16_f32 v27, v18, v19
	v_add_u32_e32 v16, v16, v114
	global_store_dwordx4 v16, v[24:27], s[0:1]
	v_fmamk_f32 v239, v238, 0x3a800000, v194
	v_rsq_f32_e32 v16, v239
	s_nop 0
	v_mov_b32_e32 v17, v16
	v_mul_f32_e32 v16, 0xbfb8aa3b, v17
	v_pk_mul_f32 v[22:23], v[12:13], v[16:17] op_sel_hi:[1,0]
	v_pk_mul_f32 v[20:21], v[14:15], v[16:17] op_sel_hi:[1,0]
	v_exp_f32_e32 v17, v22
	s_and_b64 vcc, exec, s[4:5]
	v_fma_f32 v17, v17, v239, v239
	v_rcp_f32_e32 v22, v17
	v_exp_f32_e32 v17, v23
	s_nop 0
	v_fma_f32 v17, v17, v239, v239
	v_rcp_f32_e32 v23, v17
	v_exp_f32_e32 v17, v20
	s_nop 0
	v_fma_f32 v17, v17, v239, v239
	v_rcp_f32_e32 v20, v17
	v_exp_f32_e32 v17, v21
	v_pk_mul_f32 v[8:9], v[8:9], v[22:23]
	v_fma_f32 v17, v17, v239, v239
	v_rcp_f32_e32 v21, v17
	v_cvt_pk_bf16_f32 v8, v8, v9
	v_pk_mul_f32 v[10:11], v[10:11], v[20:21]
	v_cvt_pk_bf16_f32 v9, v10, v11
	v_pk_mul_f32 v[12:13], v[4:5], v[16:17] op_sel_hi:[1,0]
	v_pk_mul_f32 v[10:11], v[6:7], v[16:17] op_sel_hi:[1,0]
	v_exp_f32_e32 v12, v12
	v_exp_f32_e32 v13, v13
	v_exp_f32_e32 v10, v10
	v_exp_f32_e32 v11, v11
	v_fma_f32 v12, v12, v239, v239
	v_fma_f32 v13, v13, v239, v239
	v_rcp_f32_e32 v12, v12
	v_rcp_f32_e32 v13, v13
	v_fma_f32 v10, v10, v239, v239
	v_fma_f32 v11, v11, v239, v239
	v_rcp_f32_e32 v10, v10
	v_rcp_f32_e32 v11, v11
	s_nop 0
	v_pk_mul_f32 v[0:1], v[0:1], v[12:13]
	v_pk_mul_f32 v[2:3], v[2:3], v[10:11]
	v_cvt_pk_bf16_f32 v10, v0, v1
	v_mul_u32_u24_e32 v0, 0x1600, v64
	v_cvt_pk_bf16_f32 v11, v2, v3
	v_add_u32_e32 v0, v0, v114
	global_store_dwordx4 v0, v[8:11], s[0:1]
	s_mov_b32 s0, s10
	s_cbranch_vccz .LBB0_399
	s_waitcnt vmcnt(0)
	s_cmpk_gt_u32 s25, 0xff
	s_cbranch_scc1 .LBB0_406
	s_barrier

.LBB0_2804:
	s_add_u32 s20, s18, 0xfffc0080
	s_addc_u32 s21, s19, -1
	s_add_i32 s42, 0, 0x10000
	ds_read_b128 v[138:141], v202
	ds_read_b128 v[142:145], v202 offset:1024
	ds_read_b128 v[146:149], v202 offset:2048
	ds_read_b128 v[154:157], v202 offset:3072
	s_cmp_eq_u32 s41, 12
	s_cselect_b32 s23, s9, s21
	s_cselect_b32 s22, s33, s20
	s_cselect_b32 s21, s11, s40
	s_cselect_b32 s20, s38, s39
	s_add_i32 m0, s17, 0xc000
	ds_read_b128 v[158:161], v152
	ds_read_b128 v[162:165], v152 offset:1024
	ds_read_b128 v[166:169], v152 offset:2048
	ds_read_b128 v[170:173], v152 offset:3072
	ds_read_b128 v[174:177], v152 offset:4096
	ds_read_b128 v[178:181], v152 offset:5120
	ds_read_b128 v[182:185], v152 offset:6144
	ds_read_b128 v[186:189], v152 offset:7168
	global_load_lds_dwordx4 v136, s[18:19]
	s_add_i32 m0, s17, 0xe000
	s_nop 0
	global_load_lds_dwordx4 v134, s[18:19]
	s_waitcnt lgkmcnt(8)
	s_barrier
	s_waitcnt lgkmcnt(0)
	v_mfma_f32_16x16x32_bf16 v[124:127], v[138:141], v[158:161], v[124:127]
	v_mfma_f32_16x16x32_bf16 v[116:119], v[146:149], v[158:161], v[116:119]
	v_mfma_f32_16x16x32_bf16 v[108:111], v[138:141], v[166:169], v[108:111]
	v_mfma_f32_16x16x32_bf16 v[100:103], v[146:149], v[166:169], v[100:103]
	v_mfma_f32_16x16x32_bf16 v[92:95], v[138:141], v[174:177], v[92:95]
	v_mfma_f32_16x16x32_bf16 v[84:87], v[146:149], v[174:177], v[84:87]
	v_mfma_f32_16x16x32_bf16 v[76:79], v[138:141], v[182:185], v[76:79]
	v_mfma_f32_16x16x32_bf16 v[68:71], v[146:149], v[182:185], v[68:71]
	v_mfma_f32_16x16x32_bf16 v[124:127], v[142:145], v[162:165], v[124:127]
	v_mfma_f32_16x16x32_bf16 v[116:119], v[154:157], v[162:165], v[116:119]
	v_mfma_f32_16x16x32_bf16 v[108:111], v[142:145], v[170:173], v[108:111]
	v_mfma_f32_16x16x32_bf16 v[100:103], v[154:157], v[170:173], v[100:103]
	v_mfma_f32_16x16x32_bf16 v[92:95], v[142:145], v[178:181], v[92:95]
	v_mfma_f32_16x16x32_bf16 v[84:87], v[154:157], v[178:181], v[84:87]
	v_mfma_f32_16x16x32_bf16 v[76:79], v[142:145], v[186:189], v[76:79]
	v_mfma_f32_16x16x32_bf16 v[68:71], v[154:157], v[186:189], v[68:71]
	s_barrier
	s_add_i32 s44, 0, 0x14000
	s_add_i32 s42, s42, s28
	s_mov_b32 m0, s42
	ds_read_b128 v[198:201], v203
	ds_read_b128 v[206:209], v203 offset:1024
	ds_read_b128 v[210:213], v203 offset:2048
	ds_read_b128 v[214:217], v203 offset:3072
	global_load_lds_dwordx4 v192, s[20:21]
	s_add_i32 m0, s42, 0x2000
	s_nop 0
	global_load_lds_dwordx4 v128, s[20:21]
	s_barrier
	s_waitcnt lgkmcnt(0)
	v_mfma_f32_16x16x32_bf16 v[120:123], v[198:201], v[158:161], v[120:123]
	v_mfma_f32_16x16x32_bf16 v[112:115], v[210:213], v[158:161], v[112:115]
	v_mfma_f32_16x16x32_bf16 v[104:107], v[198:201], v[166:169], v[104:107]
	v_mfma_f32_16x16x32_bf16 v[96:99], v[210:213], v[166:169], v[96:99]
	v_mfma_f32_16x16x32_bf16 v[88:91], v[198:201], v[174:177], v[88:91]
	v_mfma_f32_16x16x32_bf16 v[80:83], v[210:213], v[174:177], v[80:83]
	v_mfma_f32_16x16x32_bf16 v[72:75], v[198:201], v[182:185], v[72:75]
	v_mfma_f32_16x16x32_bf16 v[64:67], v[210:213], v[182:185], v[64:67]
	v_mfma_f32_16x16x32_bf16 v[120:123], v[206:209], v[162:165], v[120:123]
	v_mfma_f32_16x16x32_bf16 v[112:115], v[214:217], v[162:165], v[112:115]
	v_mfma_f32_16x16x32_bf16 v[104:107], v[206:209], v[170:173], v[104:107]
	v_mfma_f32_16x16x32_bf16 v[96:99], v[214:217], v[170:173], v[96:99]
	v_mfma_f32_16x16x32_bf16 v[88:91], v[206:209], v[178:181], v[88:91]
	v_mfma_f32_16x16x32_bf16 v[80:83], v[214:217], v[178:181], v[80:83]
	v_mfma_f32_16x16x32_bf16 v[72:75], v[206:209], v[186:189], v[72:75]
	v_mfma_f32_16x16x32_bf16 v[64:67], v[214:217], v[186:189], v[64:67]
	s_mov_b32 m0, s17
	s_add_u32 vcc_lo, s22, 0x80
	s_addc_u32 vcc_hi, s23, 0
	s_barrier
	ds_read_b128 v[158:161], v152 offset:16384
	ds_read_b128 v[162:165], v152 offset:17408
	ds_read_b128 v[166:169], v152 offset:18432
	ds_read_b128 v[170:173], v152 offset:19456
	ds_read_b128 v[174:177], v152 offset:20480
	ds_read_b128 v[178:181], v152 offset:21504
	ds_read_b128 v[182:185], v152 offset:22528
	ds_read_b128 v[186:189], v152 offset:23552
	global_load_lds_dwordx4 v132, s[22:23]
	s_mov_b32 m0, s29
	s_nop 0
	global_load_lds_dwordx4 v130, s[22:23]
	s_barrier
	s_waitcnt lgkmcnt(0)
	v_mfma_f32_16x16x32_bf16 v[60:63], v[138:141], v[158:161], v[60:63]
	v_mfma_f32_16x16x32_bf16 v[52:55], v[146:149], v[158:161], v[52:55]
	v_mfma_f32_16x16x32_bf16 v[44:47], v[138:141], v[166:169], v[44:47]
	v_mfma_f32_16x16x32_bf16 v[36:39], v[146:149], v[166:169], v[36:39]
	v_mfma_f32_16x16x32_bf16 v[28:31], v[138:141], v[174:177], v[28:31]
	v_mfma_f32_16x16x32_bf16 v[20:23], v[146:149], v[174:177], v[20:23]
	v_mfma_f32_16x16x32_bf16 v[12:15], v[138:141], v[182:185], v[12:15]
	v_mfma_f32_16x16x32_bf16 v[4:7], v[146:149], v[182:185], v[4:7]
	v_mfma_f32_16x16x32_bf16 v[60:63], v[142:145], v[162:165], v[60:63]
	v_mfma_f32_16x16x32_bf16 v[52:55], v[154:157], v[162:165], v[52:55]
	v_mfma_f32_16x16x32_bf16 v[44:47], v[142:145], v[170:173], v[44:47]
	v_mfma_f32_16x16x32_bf16 v[36:39], v[154:157], v[170:173], v[36:39]
	v_mfma_f32_16x16x32_bf16 v[28:31], v[142:145], v[178:181], v[28:31]
	v_mfma_f32_16x16x32_bf16 v[20:23], v[154:157], v[178:181], v[20:23]
	v_mfma_f32_16x16x32_bf16 v[12:15], v[142:145], v[186:189], v[12:15]
	v_mfma_f32_16x16x32_bf16 v[4:7], v[154:157], v[186:189], v[4:7]
	s_barrier
	s_add_u32 s42, s20, 0x40000
	s_addc_u32 s43, s21, 0
	s_add_i32 s44, s44, s28
	s_mov_b32 m0, s44
	s_nop 0
	global_load_lds_dwordx4 v192, s[42:43]
	s_add_i32 m0, s44, 0x2000
	s_nop 0
	global_load_lds_dwordx4 v128, s[42:43]
	s_waitcnt vmcnt(6)
	s_barrier
	v_mfma_f32_16x16x32_bf16 v[56:59], v[198:201], v[158:161], v[56:59]
	v_mfma_f32_16x16x32_bf16 v[48:51], v[210:213], v[158:161], v[48:51]
	v_mfma_f32_16x16x32_bf16 v[40:43], v[198:201], v[166:169], v[40:43]
	v_mfma_f32_16x16x32_bf16 v[32:35], v[210:213], v[166:169], v[32:35]
	v_mfma_f32_16x16x32_bf16 v[24:27], v[198:201], v[174:177], v[24:27]
	v_mfma_f32_16x16x32_bf16 v[16:19], v[210:213], v[174:177], v[16:19]
	v_mfma_f32_16x16x32_bf16 v[8:11], v[198:201], v[182:185], v[8:11]
	v_mfma_f32_16x16x32_bf16 v[0:3], v[210:213], v[182:185], v[0:3]
	v_mfma_f32_16x16x32_bf16 v[56:59], v[206:209], v[162:165], v[56:59]
	v_mfma_f32_16x16x32_bf16 v[48:51], v[214:217], v[162:165], v[48:51]
	v_mfma_f32_16x16x32_bf16 v[40:43], v[206:209], v[170:173], v[40:43]
	v_mfma_f32_16x16x32_bf16 v[32:35], v[214:217], v[170:173], v[32:35]
	v_mfma_f32_16x16x32_bf16 v[24:27], v[206:209], v[178:181], v[24:27]
	v_mfma_f32_16x16x32_bf16 v[16:19], v[214:217], v[178:181], v[16:19]
	v_mfma_f32_16x16x32_bf16 v[8:11], v[206:209], v[186:189], v[8:11]
	v_mfma_f32_16x16x32_bf16 v[0:3], v[214:217], v[186:189], v[0:3]
	s_add_i32 s42, 0, 0x18000
	s_barrier
	ds_read_b128 v[138:141], v204
	ds_read_b128 v[142:145], v204 offset:1024
	ds_read_b128 v[146:149], v204 offset:2048
	ds_read_b128 v[154:157], v204 offset:3072
	s_add_u32 s22, s22, 0x40000
	s_addc_u32 s23, s23, 0
	s_mov_b32 m0, s30
	ds_read_b128 v[158:161], v152 offset:32768
	ds_read_b128 v[162:165], v152 offset:33792
	ds_read_b128 v[166:169], v152 offset:34816
	ds_read_b128 v[170:173], v152 offset:35840
	ds_read_b128 v[174:177], v152 offset:36864
	ds_read_b128 v[178:181], v152 offset:37888
	ds_read_b128 v[182:185], v152 offset:38912
	ds_read_b128 v[186:189], v152 offset:39936
	global_load_lds_dwordx4 v132, s[22:23]
	s_mov_b32 m0, s31
	s_nop 0
	global_load_lds_dwordx4 v130, s[22:23]
	s_waitcnt lgkmcnt(8)
	s_barrier
	s_waitcnt lgkmcnt(0)
	v_mfma_f32_16x16x32_bf16 v[124:127], v[138:141], v[158:161], v[124:127]
	v_mfma_f32_16x16x32_bf16 v[116:119], v[146:149], v[158:161], v[116:119]
	v_mfma_f32_16x16x32_bf16 v[108:111], v[138:141], v[166:169], v[108:111]
	v_mfma_f32_16x16x32_bf16 v[100:103], v[146:149], v[166:169], v[100:103]
	v_mfma_f32_16x16x32_bf16 v[92:95], v[138:141], v[174:177], v[92:95]
	v_mfma_f32_16x16x32_bf16 v[84:87], v[146:149], v[174:177], v[84:87]
	v_mfma_f32_16x16x32_bf16 v[76:79], v[138:141], v[182:185], v[76:79]
	v_mfma_f32_16x16x32_bf16 v[68:71], v[146:149], v[182:185], v[68:71]
	v_mfma_f32_16x16x32_bf16 v[124:127], v[142:145], v[162:165], v[124:127]
	v_mfma_f32_16x16x32_bf16 v[116:119], v[154:157], v[162:165], v[116:119]
	v_mfma_f32_16x16x32_bf16 v[108:111], v[142:145], v[170:173], v[108:111]
	v_mfma_f32_16x16x32_bf16 v[100:103], v[154:157], v[170:173], v[100:103]
	v_mfma_f32_16x16x32_bf16 v[92:95], v[142:145], v[178:181], v[92:95]
	v_mfma_f32_16x16x32_bf16 v[84:87], v[154:157], v[178:181], v[84:87]
	v_mfma_f32_16x16x32_bf16 v[76:79], v[142:145], v[186:189], v[76:79]
	v_mfma_f32_16x16x32_bf16 v[68:71], v[154:157], v[186:189], v[68:71]
	s_barrier
	s_add_i32 s22, 0, 0x1c000
	s_add_i32 s23, s42, s28
	s_add_u32 s100, s20, 0x80
	s_addc_u32 s101, s21, 0
	s_mov_b32 m0, s23
	ds_read_b128 v[198:201], v205
	ds_read_b128 v[206:209], v205 offset:1024
	ds_read_b128 v[210:213], v205 offset:2048
	ds_read_b128 v[214:217], v205 offset:3072
	global_load_lds_dwordx4 v192, s[100:101]
	s_add_i32 m0, s23, 0x2000
	s_nop 0
	global_load_lds_dwordx4 v128, s[100:101]
	s_barrier
	s_waitcnt lgkmcnt(0)
	v_mfma_f32_16x16x32_bf16 v[120:123], v[198:201], v[158:161], v[120:123]
	v_mfma_f32_16x16x32_bf16 v[112:115], v[210:213], v[158:161], v[112:115]
	v_mfma_f32_16x16x32_bf16 v[104:107], v[198:201], v[166:169], v[104:107]
	v_mfma_f32_16x16x32_bf16 v[96:99], v[210:213], v[166:169], v[96:99]
	v_mfma_f32_16x16x32_bf16 v[88:91], v[198:201], v[174:177], v[88:91]
	v_mfma_f32_16x16x32_bf16 v[80:83], v[210:213], v[174:177], v[80:83]
	v_mfma_f32_16x16x32_bf16 v[72:75], v[198:201], v[182:185], v[72:75]
	v_mfma_f32_16x16x32_bf16 v[64:67], v[210:213], v[182:185], v[64:67]
	v_mfma_f32_16x16x32_bf16 v[120:123], v[206:209], v[162:165], v[120:123]
	v_mfma_f32_16x16x32_bf16 v[112:115], v[214:217], v[162:165], v[112:115]
	v_mfma_f32_16x16x32_bf16 v[104:107], v[206:209], v[170:173], v[104:107]
	v_mfma_f32_16x16x32_bf16 v[96:99], v[214:217], v[170:173], v[96:99]
	v_mfma_f32_16x16x32_bf16 v[88:91], v[206:209], v[178:181], v[88:91]
	v_mfma_f32_16x16x32_bf16 v[80:83], v[214:217], v[178:181], v[80:83]
	v_mfma_f32_16x16x32_bf16 v[72:75], v[206:209], v[186:189], v[72:75]
	v_mfma_f32_16x16x32_bf16 v[64:67], v[214:217], v[186:189], v[64:67]
	s_mov_b32 m0, s34
	s_barrier
	ds_read_b128 v[158:161], v152 offset:49152
	ds_read_b128 v[162:165], v152 offset:50176
	ds_read_b128 v[166:169], v152 offset:51200
	ds_read_b128 v[170:173], v152 offset:52224
	ds_read_b128 v[174:177], v152 offset:53248
	ds_read_b128 v[178:181], v152 offset:54272
	ds_read_b128 v[182:185], v152 offset:55296
	ds_read_b128 v[186:189], v152 offset:56320
	global_load_lds_dwordx4 v132, vcc
	s_mov_b32 m0, s35
	s_nop 0
	global_load_lds_dwordx4 v130, vcc
	s_barrier
	s_waitcnt lgkmcnt(0)
	v_mfma_f32_16x16x32_bf16 v[60:63], v[138:141], v[158:161], v[60:63]
	v_mfma_f32_16x16x32_bf16 v[52:55], v[146:149], v[158:161], v[52:55]
	v_mfma_f32_16x16x32_bf16 v[44:47], v[138:141], v[166:169], v[44:47]
	v_mfma_f32_16x16x32_bf16 v[36:39], v[146:149], v[166:169], v[36:39]
	v_mfma_f32_16x16x32_bf16 v[28:31], v[138:141], v[174:177], v[28:31]
	v_mfma_f32_16x16x32_bf16 v[20:23], v[146:149], v[174:177], v[20:23]
	v_mfma_f32_16x16x32_bf16 v[12:15], v[138:141], v[182:185], v[12:15]
	v_mfma_f32_16x16x32_bf16 v[4:7], v[146:149], v[182:185], v[4:7]
	v_mfma_f32_16x16x32_bf16 v[60:63], v[142:145], v[162:165], v[60:63]
	v_mfma_f32_16x16x32_bf16 v[52:55], v[154:157], v[162:165], v[52:55]
	v_mfma_f32_16x16x32_bf16 v[44:47], v[142:145], v[170:173], v[44:47]
	v_mfma_f32_16x16x32_bf16 v[36:39], v[154:157], v[170:173], v[36:39]
	v_mfma_f32_16x16x32_bf16 v[28:31], v[142:145], v[178:181], v[28:31]
	v_mfma_f32_16x16x32_bf16 v[20:23], v[154:157], v[178:181], v[20:23]
	v_mfma_f32_16x16x32_bf16 v[12:15], v[142:145], v[186:189], v[12:15]
	v_mfma_f32_16x16x32_bf16 v[4:7], v[154:157], v[186:189], v[4:7]
	s_barrier
	s_add_u32 s20, s20, 0x40080
	s_addc_u32 s21, s21, 0
	s_add_i32 s22, s22, s28
	s_mov_b32 m0, s22
	s_nop 0
	global_load_lds_dwordx4 v192, s[20:21]
	s_add_i32 m0, s22, 0x2000
	s_nop 0
	global_load_lds_dwordx4 v128, s[20:21]
	s_waitcnt vmcnt(6)
	s_barrier
	v_mfma_f32_16x16x32_bf16 v[56:59], v[198:201], v[158:161], v[56:59]
	v_mfma_f32_16x16x32_bf16 v[48:51], v[210:213], v[158:161], v[48:51]
	v_mfma_f32_16x16x32_bf16 v[40:43], v[198:201], v[166:169], v[40:43]
	v_mfma_f32_16x16x32_bf16 v[32:35], v[210:213], v[166:169], v[32:35]
	v_mfma_f32_16x16x32_bf16 v[24:27], v[198:201], v[174:177], v[24:27]
	v_mfma_f32_16x16x32_bf16 v[16:19], v[210:213], v[174:177], v[16:19]
	v_mfma_f32_16x16x32_bf16 v[8:11], v[198:201], v[182:185], v[8:11]
	v_mfma_f32_16x16x32_bf16 v[0:3], v[210:213], v[182:185], v[0:3]
	v_mfma_f32_16x16x32_bf16 v[56:59], v[206:209], v[162:165], v[56:59]
	v_mfma_f32_16x16x32_bf16 v[48:51], v[214:217], v[162:165], v[48:51]
	v_mfma_f32_16x16x32_bf16 v[40:43], v[206:209], v[170:173], v[40:43]
	v_mfma_f32_16x16x32_bf16 v[32:35], v[214:217], v[170:173], v[32:35]
	v_mfma_f32_16x16x32_bf16 v[24:27], v[206:209], v[178:181], v[24:27]
	v_mfma_f32_16x16x32_bf16 v[16:19], v[214:217], v[178:181], v[16:19]
	v_mfma_f32_16x16x32_bf16 v[8:11], v[206:209], v[186:189], v[8:11]
	v_mfma_f32_16x16x32_bf16 v[0:3], v[214:217], v[186:189], v[0:3]
	s_add_i32 s41, s41, 2
	s_add_u32 s39, s39, 0x100
	s_addc_u32 s40, s40, 0
	s_add_u32 s18, s18, 0x100
	s_addc_u32 s19, s19, 0
	s_cmp_gt_u32 s41, 13
	s_barrier
	s_cbranch_scc0 .LBB0_2804
	v_mov_b32_e32 v139, v252
	s_lshl_b32 s11, s16, 8
	v_readfirstlane_b32 s9, v139
	s_ashr_i32 s16, s9, 2
	s_andn2_b32 s16, s16, 63
	s_lshr_b32 s9, s9, 1
	s_add_i32 s16, s16, s11
	s_lshl_b32 s11, s37, 7
	s_and_b32 s9, s9, 0x60
	v_and_or_b32 v138, v139, 15, s16
	s_or_b32 s9, s9, s11
	v_lshrrev_b32_e32 v139, 1, v139
	v_and_or_b32 v148, v139, 24, s9
	v_ashrrev_i32_e32 v139, 31, v138
	v_lshl_add_u64 v[140:141], v[138:139], 2, s[6:7]
	v_or_b32_e32 v146, 16, v138
	v_ashrrev_i32_e32 v147, 31, v146
	v_lshl_add_u64 v[142:143], v[146:147], 2, s[6:7]
	v_or_b32_e32 v144, 32, v138
	v_ashrrev_i32_e32 v145, 31, v144
	v_lshl_add_u64 v[142:143], v[144:145], 2, s[6:7]
	v_or_b32_e32 v142, 48, v138
	v_ashrrev_i32_e32 v143, 31, v142
	v_lshl_add_u64 v[154:155], v[142:143], 2, s[6:7]
	v_pk_mul_f32 v[120:121], v[124:125], v[120:121]
	v_pk_mul_f32 v[122:123], v[126:127], v[122:123]
	v_pk_mul_f32 v[112:113], v[116:117], v[112:113]
	v_pk_mul_f32 v[114:115], v[118:119], v[114:115]
	v_ashrrev_i32_e32 v149, 31, v148
	s_movk_i32 s9, 0x1600
	v_pk_mul_f32 v[104:105], v[108:109], v[104:105]
	v_pk_mul_f32 v[106:107], v[110:111], v[106:107]
	v_pk_mul_f32 v[96:97], v[100:101], v[96:97]
	v_pk_mul_f32 v[98:99], v[102:103], v[98:99]
	v_pk_mul_f32 v[88:89], v[92:93], v[88:89]
	v_pk_mul_f32 v[90:91], v[94:95], v[90:91]
	v_pk_mul_f32 v[80:81], v[84:85], v[80:81]
	v_pk_mul_f32 v[82:83], v[86:87], v[82:83]
	v_pk_mul_f32 v[72:73], v[76:77], v[72:73]
	v_pk_mul_f32 v[74:75], v[78:79], v[74:75]
	v_pk_mul_f32 v[64:65], v[68:69], v[64:65]
	v_pk_mul_f32 v[66:67], v[70:71], v[66:67]
	v_pk_mul_f32 v[56:57], v[60:61], v[56:57]
	v_pk_mul_f32 v[58:59], v[62:63], v[58:59]
	v_pk_mul_f32 v[48:49], v[52:53], v[48:49]
	v_pk_mul_f32 v[50:51], v[54:55], v[50:51]
	v_pk_mul_f32 v[40:41], v[44:45], v[40:41]
	v_pk_mul_f32 v[42:43], v[46:47], v[42:43]
	v_pk_mul_f32 v[32:33], v[36:37], v[32:33]
	v_pk_mul_f32 v[34:35], v[38:39], v[34:35]
	v_pk_mul_f32 v[24:25], v[28:29], v[24:25]
	v_pk_mul_f32 v[26:27], v[30:31], v[26:27]
	v_pk_mul_f32 v[16:17], v[20:21], v[16:17]
	v_pk_mul_f32 v[18:19], v[22:23], v[18:19]
	v_pk_mul_f32 v[8:9], v[12:13], v[8:9]
	v_pk_mul_f32 v[10:11], v[14:15], v[10:11]
	v_pk_mul_f32 v[0:1], v[4:5], v[0:1]
	v_pk_mul_f32 v[2:3], v[6:7], v[2:3]
	s_mov_b32 s37, s10
	s_mov_b32 s16, s8
	s_mov_b64 s[20:21], s[12:13]
	v_fmamk_f32 v239, v231, 0x3a800000, v194
	v_rsq_f32_e32 v143, v239
	s_nop 0
	v_mul_f32_e32 v154, 0xbfb8aa3b, v143
	v_pk_mul_f32 v[158:159], v[124:125], v[154:155] op_sel_hi:[1,0]
	v_exp_f32_e32 v143, v158
	v_pk_mul_f32 v[156:157], v[126:127], v[154:155] op_sel_hi:[1,0]
	v_fma_f32 v143, v143, v239, v239
	v_rcp_f32_e32 v158, v143
	v_exp_f32_e32 v143, v159
	s_nop 0
	v_fma_f32 v143, v143, v239, v239
	v_rcp_f32_e32 v159, v143
	v_exp_f32_e32 v143, v156
	s_nop 0
	v_fma_f32 v143, v143, v239, v239
	v_rcp_f32_e32 v156, v143
	v_exp_f32_e32 v143, v157
	v_pk_mul_f32 v[120:121], v[120:121], v[158:159]
	v_fma_f32 v143, v143, v239, v239
	v_rcp_f32_e32 v157, v143
	v_cvt_pk_bf16_f32 v120, v120, v121
	v_pk_mul_f32 v[122:123], v[122:123], v[156:157]
	v_cvt_pk_bf16_f32 v121, v122, v123
	v_pk_mul_f32 v[124:125], v[116:117], v[154:155] op_sel_hi:[1,0]
	v_pk_mul_f32 v[122:123], v[118:119], v[154:155] op_sel_hi:[1,0]
	v_exp_f32_e32 v124, v124
	v_exp_f32_e32 v125, v125
	v_exp_f32_e32 v122, v122
	v_exp_f32_e32 v123, v123
	v_fma_f32 v124, v124, v239, v239
	v_fma_f32 v125, v125, v239, v239
	v_rcp_f32_e32 v124, v124
	v_rcp_f32_e32 v125, v125
	v_fma_f32 v122, v122, v239, v239
	v_fma_f32 v123, v123, v239, v239
	v_rcp_f32_e32 v122, v122
	v_rcp_f32_e32 v123, v123
	s_nop 0
	v_pk_mul_f32 v[112:113], v[112:113], v[124:125]
	v_pk_mul_f32 v[114:115], v[114:115], v[122:123]
	v_cvt_pk_bf16_f32 v122, v112, v113
	v_cvt_pk_bf16_f32 v123, v114, v115
	v_mul_u32_u24_e32 v116, 0x1600, v138
	v_lshlrev_b32_e32 v114, 1, v148
	v_add_u32_e32 v116, v116, v114
	global_store_dwordx4 v116, v[120:123], s[4:5]
	v_fmamk_f32 v239, v232, 0x3a800000, v194
	v_rsq_f32_e32 v116, v239
	s_nop 0
	v_mul_f32_e32 v118, 0xbfb8aa3b, v116
	v_pk_mul_f32 v[122:123], v[108:109], v[118:119] op_sel_hi:[1,0]
	v_pk_mul_f32 v[120:121], v[110:111], v[118:119] op_sel_hi:[1,0]
	v_exp_f32_e32 v117, v122
	s_nop 0
	v_fma_f32 v117, v117, v239, v239
	v_rcp_f32_e32 v122, v117
	v_exp_f32_e32 v117, v123
	s_nop 0
	v_fma_f32 v117, v117, v239, v239
	v_rcp_f32_e32 v123, v117
	v_exp_f32_e32 v117, v120
	s_nop 0
	v_fma_f32 v117, v117, v239, v239
	v_rcp_f32_e32 v120, v117
	v_exp_f32_e32 v117, v121
	s_nop 0
	v_fma_f32 v117, v117, v239, v239
	v_rcp_f32_e32 v121, v117
	s_nop 0
	v_pk_mul_f32 v[104:105], v[104:105], v[122:123]
	v_pk_mul_f32 v[106:107], v[106:107], v[120:121]
	v_cvt_pk_bf16_f32 v104, v104, v105
	v_cvt_pk_bf16_f32 v105, v106, v107
	v_pk_mul_f32 v[108:109], v[100:101], v[118:119] op_sel_hi:[1,0]
	v_pk_mul_f32 v[106:107], v[102:103], v[118:119] op_sel_hi:[1,0]
	v_exp_f32_e32 v108, v108
	v_exp_f32_e32 v109, v109
	v_exp_f32_e32 v106, v106
	v_exp_f32_e32 v107, v107
	v_fma_f32 v108, v108, v239, v239
	v_fma_f32 v109, v109, v239, v239
	v_rcp_f32_e32 v108, v108
	v_rcp_f32_e32 v109, v109
	v_fma_f32 v106, v106, v239, v239
	v_fma_f32 v107, v107, v239, v239
	v_rcp_f32_e32 v106, v106
	v_rcp_f32_e32 v107, v107
	s_nop 0
	v_pk_mul_f32 v[96:97], v[96:97], v[108:109]
	v_pk_mul_f32 v[98:99], v[98:99], v[106:107]
	v_cvt_pk_bf16_f32 v106, v96, v97
	v_mul_u32_u24_e32 v96, 0x1600, v146
	v_cvt_pk_bf16_f32 v107, v98, v99
	v_add_u32_e32 v96, v96, v114
	global_store_dwordx4 v96, v[104:107], s[4:5]
	v_fmamk_f32 v239, v233, 0x3a800000, v194
	v_rsq_f32_e32 v96, v239
	s_nop 0
	v_mov_b32_e32 v97, v96
	v_mul_f32_e32 v96, 0xbfb8aa3b, v97
	v_pk_mul_f32 v[102:103], v[92:93], v[96:97] op_sel_hi:[1,0]
	v_pk_mul_f32 v[100:101], v[94:95], v[96:97] op_sel_hi:[1,0]
	v_exp_f32_e32 v97, v102
	s_nop 0
	v_fma_f32 v97, v97, v239, v239
	v_rcp_f32_e32 v102, v97
	v_exp_f32_e32 v97, v103
	s_nop 0
	v_fma_f32 v97, v97, v239, v239
	v_rcp_f32_e32 v103, v97
	v_exp_f32_e32 v97, v100
	s_nop 0
	v_fma_f32 v97, v97, v239, v239
	v_rcp_f32_e32 v100, v97
	v_exp_f32_e32 v97, v101
	v_pk_mul_f32 v[88:89], v[88:89], v[102:103]
	v_fma_f32 v97, v97, v239, v239
	v_rcp_f32_e32 v101, v97
	v_cvt_pk_bf16_f32 v88, v88, v89
	v_pk_mul_f32 v[90:91], v[90:91], v[100:101]
	v_cvt_pk_bf16_f32 v89, v90, v91
	v_pk_mul_f32 v[92:93], v[84:85], v[96:97] op_sel_hi:[1,0]
	v_pk_mul_f32 v[90:91], v[86:87], v[96:97] op_sel_hi:[1,0]
	v_exp_f32_e32 v92, v92
	v_exp_f32_e32 v93, v93
	v_exp_f32_e32 v90, v90
	v_exp_f32_e32 v91, v91
	v_fma_f32 v92, v92, v239, v239
	v_fma_f32 v93, v93, v239, v239
	v_rcp_f32_e32 v92, v92
	v_rcp_f32_e32 v93, v93
	v_fma_f32 v90, v90, v239, v239
	v_fma_f32 v91, v91, v239, v239
	v_rcp_f32_e32 v90, v90
	v_rcp_f32_e32 v91, v91
	s_nop 0
	v_pk_mul_f32 v[80:81], v[80:81], v[92:93]
	v_pk_mul_f32 v[82:83], v[82:83], v[90:91]
	v_cvt_pk_bf16_f32 v90, v80, v81
	v_mul_u32_u24_e32 v80, 0x1600, v144
	v_cvt_pk_bf16_f32 v91, v82, v83
	v_add_u32_e32 v80, v80, v114
	global_store_dwordx4 v80, v[88:91], s[4:5]
	v_fmamk_f32 v239, v234, 0x3a800000, v194
	v_rsq_f32_e32 v80, v239
	s_nop 0
	v_mov_b32_e32 v81, v80
	v_mul_f32_e32 v80, 0xbfb8aa3b, v81
	v_pk_mul_f32 v[86:87], v[76:77], v[80:81] op_sel_hi:[1,0]
	v_pk_mul_f32 v[84:85], v[78:79], v[80:81] op_sel_hi:[1,0]
	v_exp_f32_e32 v81, v86
	s_nop 0
	v_fma_f32 v81, v81, v239, v239
	v_rcp_f32_e32 v86, v81
	v_exp_f32_e32 v81, v87
	s_nop 0
	v_fma_f32 v81, v81, v239, v239
	v_rcp_f32_e32 v87, v81
	v_exp_f32_e32 v81, v84
	s_nop 0
	v_fma_f32 v81, v81, v239, v239
	v_rcp_f32_e32 v84, v81
	v_exp_f32_e32 v81, v85
	v_pk_mul_f32 v[72:73], v[72:73], v[86:87]
	v_fma_f32 v81, v81, v239, v239
	v_rcp_f32_e32 v85, v81
	v_cvt_pk_bf16_f32 v72, v72, v73
	v_pk_mul_f32 v[74:75], v[74:75], v[84:85]
	v_cvt_pk_bf16_f32 v73, v74, v75
	v_pk_mul_f32 v[76:77], v[68:69], v[80:81] op_sel_hi:[1,0]
	v_pk_mul_f32 v[74:75], v[70:71], v[80:81] op_sel_hi:[1,0]
	v_exp_f32_e32 v76, v76
	v_exp_f32_e32 v77, v77
	v_exp_f32_e32 v74, v74
	v_exp_f32_e32 v75, v75
	v_fma_f32 v76, v76, v239, v239
	v_fma_f32 v77, v77, v239, v239
	v_rcp_f32_e32 v76, v76
	v_rcp_f32_e32 v77, v77
	v_fma_f32 v74, v74, v239, v239
	v_fma_f32 v75, v75, v239, v239
	v_rcp_f32_e32 v74, v74
	v_rcp_f32_e32 v75, v75
	s_nop 0
	v_pk_mul_f32 v[64:65], v[64:65], v[76:77]
	v_add_u32_e32 v69, 0x90, v138
	v_pk_mul_f32 v[66:67], v[66:67], v[74:75]
	v_cvt_pk_bf16_f32 v74, v64, v65
	v_mul_u32_u24_e32 v64, 0x1600, v142
	v_cvt_pk_bf16_f32 v75, v66, v67
	v_add_u32_e32 v64, v64, v114
	global_store_dwordx4 v64, v[72:75], s[4:5]
	v_add_u32_e32 v67, 0x80, v138
	v_add_u32_e32 v66, 0xa0, v138
	v_add_u32_e32 v64, 0xb0, v138
	v_fmamk_f32 v239, v235, 0x3a800000, v194
	v_rsq_f32_e32 v68, v239
	s_nop 0
	v_mov_b32_e32 v70, v68
	v_mul_f32_e32 v68, 0xbfb8aa3b, v70
	v_pk_mul_f32 v[74:75], v[60:61], v[68:69] op_sel_hi:[1,0]
	v_pk_mul_f32 v[72:73], v[62:63], v[68:69] op_sel_hi:[1,0]
	v_exp_f32_e32 v74, v74
	v_exp_f32_e32 v75, v75
	v_exp_f32_e32 v72, v72
	v_exp_f32_e32 v73, v73
	v_fma_f32 v74, v74, v239, v239
	v_fma_f32 v75, v75, v239, v239
	v_rcp_f32_e32 v74, v74
	v_rcp_f32_e32 v75, v75
	v_fma_f32 v72, v72, v239, v239
	v_fma_f32 v73, v73, v239, v239
	v_rcp_f32_e32 v72, v72
	v_rcp_f32_e32 v73, v73
	s_nop 0
	s_nop 0
	v_pk_mul_f32 v[56:57], v[56:57], v[74:75]
	v_pk_mul_f32 v[58:59], v[58:59], v[72:73]
	v_cvt_pk_bf16_f32 v56, v56, v57
	v_cvt_pk_bf16_f32 v57, v58, v59
	v_pk_mul_f32 v[60:61], v[52:53], v[68:69] op_sel_hi:[1,0]
	v_pk_mul_f32 v[58:59], v[54:55], v[68:69] op_sel_hi:[1,0]
	v_exp_f32_e32 v60, v60
	v_exp_f32_e32 v61, v61
	v_exp_f32_e32 v58, v58
	v_exp_f32_e32 v59, v59
	v_fma_f32 v60, v60, v239, v239
	v_fma_f32 v61, v61, v239, v239
	v_rcp_f32_e32 v60, v60
	v_rcp_f32_e32 v61, v61
	v_fma_f32 v58, v58, v239, v239
	v_fma_f32 v59, v59, v239, v239
	v_rcp_f32_e32 v58, v58
	v_rcp_f32_e32 v59, v59
	s_nop 0
	v_pk_mul_f32 v[48:49], v[48:49], v[60:61]
	v_pk_mul_f32 v[50:51], v[50:51], v[58:59]
	v_cvt_pk_bf16_f32 v58, v48, v49
	v_mul_u32_u24_e32 v48, 0x1600, v67
	v_cvt_pk_bf16_f32 v59, v50, v51
	v_add_u32_e32 v48, v48, v114
	global_store_dwordx4 v48, v[56:59], s[4:5]
	v_fmamk_f32 v239, v236, 0x3a800000, v194
	v_rsq_f32_e32 v48, v239
	s_nop 0
	v_mov_b32_e32 v49, v48
	v_mul_f32_e32 v48, 0xbfb8aa3b, v49
	v_pk_mul_f32 v[54:55], v[44:45], v[48:49] op_sel_hi:[1,0]
	v_pk_mul_f32 v[52:53], v[46:47], v[48:49] op_sel_hi:[1,0]
	v_exp_f32_e32 v49, v54
	s_nop 0
	v_fma_f32 v49, v49, v239, v239
	v_rcp_f32_e32 v54, v49
	v_exp_f32_e32 v49, v55
	s_nop 0
	v_fma_f32 v49, v49, v239, v239
	v_rcp_f32_e32 v55, v49
	v_exp_f32_e32 v49, v52
	s_nop 0
	v_fma_f32 v49, v49, v239, v239
	v_rcp_f32_e32 v52, v49
	v_exp_f32_e32 v49, v53
	v_pk_mul_f32 v[40:41], v[40:41], v[54:55]
	v_fma_f32 v49, v49, v239, v239
	v_rcp_f32_e32 v53, v49
	v_cvt_pk_bf16_f32 v40, v40, v41
	v_pk_mul_f32 v[42:43], v[42:43], v[52:53]
	v_cvt_pk_bf16_f32 v41, v42, v43
	v_pk_mul_f32 v[44:45], v[36:37], v[48:49] op_sel_hi:[1,0]
	v_pk_mul_f32 v[42:43], v[38:39], v[48:49] op_sel_hi:[1,0]
	v_exp_f32_e32 v44, v44
	v_exp_f32_e32 v45, v45
	v_exp_f32_e32 v42, v42
	v_exp_f32_e32 v43, v43
	v_fma_f32 v44, v44, v239, v239
	v_fma_f32 v45, v45, v239, v239
	v_rcp_f32_e32 v44, v44
	v_rcp_f32_e32 v45, v45
	v_fma_f32 v42, v42, v239, v239
	v_fma_f32 v43, v43, v239, v239
	v_rcp_f32_e32 v42, v42
	v_rcp_f32_e32 v43, v43
	s_nop 0
	v_pk_mul_f32 v[32:33], v[32:33], v[44:45]
	v_pk_mul_f32 v[34:35], v[34:35], v[42:43]
	v_cvt_pk_bf16_f32 v42, v32, v33
	v_mul_u32_u24_e32 v32, 0x1600, v69
	v_cvt_pk_bf16_f32 v43, v34, v35
	v_add_u32_e32 v32, v32, v114
	global_store_dwordx4 v32, v[40:43], s[4:5]
	v_fmamk_f32 v239, v237, 0x3a800000, v194
	v_rsq_f32_e32 v32, v239
	s_nop 0
	v_mov_b32_e32 v33, v32
	v_mul_f32_e32 v32, 0xbfb8aa3b, v33
	v_pk_mul_f32 v[38:39], v[28:29], v[32:33] op_sel_hi:[1,0]
	v_pk_mul_f32 v[36:37], v[30:31], v[32:33] op_sel_hi:[1,0]
	v_exp_f32_e32 v33, v38
	s_nop 0
	v_fma_f32 v33, v33, v239, v239
	v_rcp_f32_e32 v38, v33
	v_exp_f32_e32 v33, v39
	s_nop 0
	v_fma_f32 v33, v33, v239, v239
	v_rcp_f32_e32 v39, v33
	v_exp_f32_e32 v33, v36
	s_nop 0
	v_fma_f32 v33, v33, v239, v239
	v_rcp_f32_e32 v36, v33
	v_exp_f32_e32 v33, v37
	v_pk_mul_f32 v[24:25], v[24:25], v[38:39]
	v_fma_f32 v33, v33, v239, v239
	v_rcp_f32_e32 v37, v33
	v_cvt_pk_bf16_f32 v24, v24, v25
	v_pk_mul_f32 v[26:27], v[26:27], v[36:37]
	v_cvt_pk_bf16_f32 v25, v26, v27
	v_pk_mul_f32 v[28:29], v[20:21], v[32:33] op_sel_hi:[1,0]
	v_pk_mul_f32 v[26:27], v[22:23], v[32:33] op_sel_hi:[1,0]
	v_exp_f32_e32 v28, v28
	v_exp_f32_e32 v29, v29
	v_exp_f32_e32 v26, v26
	v_exp_f32_e32 v27, v27
	v_fma_f32 v28, v28, v239, v239
	v_fma_f32 v29, v29, v239, v239
	v_rcp_f32_e32 v28, v28
	v_rcp_f32_e32 v29, v29
	v_fma_f32 v26, v26, v239, v239
	v_fma_f32 v27, v27, v239, v239
	v_rcp_f32_e32 v26, v26
	v_rcp_f32_e32 v27, v27
	s_nop 0
	v_pk_mul_f32 v[16:17], v[16:17], v[28:29]
	v_pk_mul_f32 v[18:19], v[18:19], v[26:27]
	v_cvt_pk_bf16_f32 v26, v16, v17
	v_mul_u32_u24_e32 v16, 0x1600, v66
	v_cvt_pk_bf16_f32 v27, v18, v19
	v_add_u32_e32 v16, v16, v114
	global_store_dwordx4 v16, v[24:27], s[4:5]
	v_fmamk_f32 v239, v238, 0x3a800000, v194
	v_rsq_f32_e32 v16, v239
	s_nop 0
	v_mov_b32_e32 v17, v16
	v_mul_f32_e32 v16, 0xbfb8aa3b, v17
	v_pk_mul_f32 v[22:23], v[12:13], v[16:17] op_sel_hi:[1,0]
	v_pk_mul_f32 v[20:21], v[14:15], v[16:17] op_sel_hi:[1,0]
	v_exp_f32_e32 v17, v22
	s_and_b64 vcc, exec, s[0:1]
	v_fma_f32 v17, v17, v239, v239
	v_rcp_f32_e32 v22, v17
	v_exp_f32_e32 v17, v23
	s_nop 0
	v_fma_f32 v17, v17, v239, v239
	v_rcp_f32_e32 v23, v17
	v_exp_f32_e32 v17, v20
	s_nop 0
	v_fma_f32 v17, v17, v239, v239
	v_rcp_f32_e32 v20, v17
	v_exp_f32_e32 v17, v21
	v_pk_mul_f32 v[8:9], v[8:9], v[22:23]
	v_fma_f32 v17, v17, v239, v239
	v_rcp_f32_e32 v21, v17
	v_cvt_pk_bf16_f32 v8, v8, v9
	v_pk_mul_f32 v[10:11], v[10:11], v[20:21]
	v_cvt_pk_bf16_f32 v9, v10, v11
	v_pk_mul_f32 v[12:13], v[4:5], v[16:17] op_sel_hi:[1,0]
	v_pk_mul_f32 v[10:11], v[6:7], v[16:17] op_sel_hi:[1,0]
	v_exp_f32_e32 v12, v12
	v_exp_f32_e32 v13, v13
	v_exp_f32_e32 v10, v10
	v_exp_f32_e32 v11, v11
	v_fma_f32 v12, v12, v239, v239
	v_fma_f32 v13, v13, v239, v239
	v_rcp_f32_e32 v12, v12
	v_rcp_f32_e32 v13, v13
	v_fma_f32 v10, v10, v239, v239
	v_fma_f32 v11, v11, v239, v239
	v_rcp_f32_e32 v10, v10
	v_rcp_f32_e32 v11, v11
	s_nop 0
	v_pk_mul_f32 v[0:1], v[0:1], v[12:13]
	v_pk_mul_f32 v[2:3], v[2:3], v[10:11]
	v_cvt_pk_bf16_f32 v10, v0, v1
	v_mul_u32_u24_e32 v0, 0x1600, v64
	v_cvt_pk_bf16_f32 v11, v2, v3
	v_add_u32_e32 v0, v0, v114
	s_mov_b64 s[18:19], s[14:15]
	global_store_dwordx4 v0, v[8:11], s[4:5]
	s_cbranch_vccz .LBB0_2801
	s_waitcnt vmcnt(0)
	s_cmpk_gt_u32 s25, 0xff
	s_cbranch_scc1 .LBB0_2808
	s_barrier
